# v024 plus diff-attention epilogue: pass-1 scratch reload issued as two batches of eight loads instead of four serialized batches of four
# speedup vs baseline: 1.0015x; 1.0010x over previous
; template <int DQK, bool ROPEQ, bool ALIBI> ...
;     ...
;         const float rl = __builtin_amdgcn_rcpf(l_reg);
; #pragma unroll
;         for (int d = 0; d < 4; ++d)
; #pragma unroll
;             for (int r = 0; r < 16; ++r) o[d][r] *= rl;
; __global__ void __launch_bounds__(512, 2) mega(Args a) {
;     ...
;                 if (ntw > 0) {
;                     float ssq = 0.f;
; #pragma unroll
;                     for (int d = 0; d < 4; ++d) {
; #pragma unroll
;                         for (int r = 0; r < 16; r += 4) { const f32x4 s1 = *(const f32x4*)(sp + d * 16 + r);
; #pragma unroll
;                             for (int k = 0; k < 4; ++k) { const float x = s1[k] - lam * o[d][r + k]; o[d][r + k] = x; ssq += x * x; } }
;                         asm volatile("" ::: "memory"); }
.LBB0_1219:
	s_and_b64 vcc, exec, s[20:21]
	s_cbranch_vccz .LBB0_1168
	v_rcp_f32_e32 v66, v139
	s_mov_b32 s0, 0x800000
	v_mul_f32_e32 v68, v66, v50
	v_mul_f32_e32 v78, v66, v60
	v_mul_f32_e32 v80, v66, v64
	v_mul_f32_e32 v86, v66, v34
	v_mul_f32_e32 v89, v66, v38
	v_mul_f32_e32 v92, v66, v42
	v_mul_f32_e32 v93, v66, v43
	v_mul_f32_e32 v94, v66, v44
	v_mul_f32_e32 v95, v66, v45
	v_mul_f32_e32 v71, v66, v18
	v_mul_f32_e32 v69, v66, v19
	v_mul_f32_e32 v67, v66, v20
	v_mul_f32_e32 v64, v66, v21
	v_mul_f32_e32 v60, v66, v23
	v_mul_f32_e32 v50, v66, v26
	v_mul_f32_e32 v38, v66, v29
	v_mul_f32_e32 v34, v66, v30
	v_mul_f32_e32 v76, v66, v31
	v_mul_f32_e32 v29, v66, v32
	v_mul_f32_e32 v26, v66, v33
	v_mul_f32_e32 v75, v66, v2
	v_mul_f32_e32 v74, v66, v3
	v_mul_f32_e32 v73, v66, v4
	v_mul_f32_e32 v23, v66, v5
	global_load_dwordx4 v[100:103], v[134:135], off offset:48
	global_load_dwordx4 v[104:107], v[134:135], off offset:32
	global_load_dwordx4 v[108:111], v[134:135], off offset:16
	global_load_dwordx4 v[112:115], v[134:135], off
	global_load_dwordx4 v[116:119], v[134:135], off offset:112
	global_load_dwordx4 v[120:123], v[134:135], off offset:96
	global_load_dwordx4 v[124:127], v[134:135], off offset:80
	global_load_dwordx4 v[240:243], v[134:135], off offset:64
	v_mul_f32_e32 v51, v66, v51
	v_mul_f32_e32 v55, v66, v55
	v_mul_f32_e32 v77, v66, v58
	v_mul_f32_e32 v59, v66, v59
	v_mul_f32_e32 v61, v66, v61
	v_mul_f32_e32 v79, v66, v62
	v_mul_f32_e32 v63, v66, v63
	v_mul_f32_e32 v65, v66, v65
	v_mul_f32_e32 v72, v66, v56
	v_mul_f32_e32 v87, v66, v36
	v_mul_f32_e32 v88, v66, v37
	v_mul_f32_e32 v90, v66, v40
	v_mul_f32_e32 v91, v66, v41
	v_mul_f32_e32 v98, v66, v48
	v_mul_f32_e32 v58, v66, v24
	v_mul_f32_e32 v56, v66, v25
	v_mul_f32_e32 v41, v66, v28
	v_mul_f32_e32 v52, v66, v52
	v_mul_f32_e32 v53, v66, v53
	v_mul_f32_e32 v70, v66, v54
	v_mul_f32_e32 v57, v66, v57
	v_mul_f32_e32 v35, v66, v35
	v_mul_f32_e32 v39, v66, v39
	v_mul_f32_e32 v96, v66, v46
	v_mul_f32_e32 v97, v66, v47
	v_mul_f32_e32 v99, v66, v49
	v_mul_f32_e32 v46, v66, v27
	v_mul_f32_e32 v62, v66, v22
	v_mul_f32_e32 v22, v66, v6
	v_mul_f32_e32 v6, v66, v7
	s_waitcnt vmcnt(3)
	v_fma_f32 v28, -v130, v63, v101
	s_waitcnt vmcnt(2)
	v_fma_f32 v40, -v130, v59, v105
	s_waitcnt vmcnt(1)
	v_fma_f32 v48, -v130, v55, v109
	s_waitcnt vmcnt(0)
	v_fma_f32 v51, -v130, v51, v113
	v_fma_f32 v43, -v130, v77, v104
	v_fma_f32 v37, -v130, v78, v106
	v_fma_f32 v36, -v130, v61, v107
	v_fma_f32 v31, -v130, v79, v100
	v_fma_f32 v25, -v130, v80, v102
	v_fma_f32 v24, -v130, v65, v103
	v_fma_f32 v54, -v130, v68, v112
	v_fma_f32 v52, -v130, v52, v114
	v_fma_f32 v53, -v130, v53, v115
	v_fma_f32 v47, -v130, v70, v108
	v_fma_f32 v44, -v130, v72, v110
	v_fma_f32 v45, -v130, v57, v111
	v_mul_f32_e32 v7, v51, v51
	v_fmac_f32_e32 v7, v54, v54
	v_fmac_f32_e32 v7, v52, v52
	v_fmac_f32_e32 v7, v53, v53
	v_fmac_f32_e32 v7, v47, v47
	v_fmac_f32_e32 v7, v48, v48
	v_fmac_f32_e32 v7, v44, v44
	v_fmac_f32_e32 v7, v45, v45
	v_fmac_f32_e32 v7, v43, v43
	v_fmac_f32_e32 v7, v40, v40
	v_fmac_f32_e32 v7, v37, v37
	v_fmac_f32_e32 v7, v36, v36
	v_fmac_f32_e32 v7, v31, v31
	v_fmac_f32_e32 v7, v28, v28
	v_fmac_f32_e32 v7, v25, v25
	v_fmac_f32_e32 v7, v24, v24
	v_fma_f32 v33, -v130, v97, v117
	s_waitcnt vmcnt(2)
	v_fma_f32 v55, -v130, v92, v120
	s_waitcnt vmcnt(1)
	v_fma_f32 v63, -v130, v89, v124
	s_waitcnt vmcnt(0)
	v_fma_f32 v72, -v130, v86, v240
	v_fma_f32 v70, -v130, v35, v241
	v_fma_f32 v68, -v130, v87, v242
	v_fma_f32 v65, -v130, v88, v243
	v_fma_f32 v61, -v130, v39, v125
	v_fma_f32 v59, -v130, v90, v126
	v_fma_f32 v57, -v130, v91, v127
	v_fma_f32 v49, -v130, v93, v121
	v_fma_f32 v42, -v130, v94, v122
	v_fma_f32 v39, -v130, v95, v123
	v_fma_f32 v35, -v130, v96, v116
	v_fma_f32 v30, -v130, v98, v118
	v_fma_f32 v27, -v130, v99, v119
	global_load_dwordx4 v[100:103], v[134:135], off offset:176
	global_load_dwordx4 v[104:107], v[134:135], off offset:160
	global_load_dwordx4 v[108:111], v[134:135], off offset:144
	global_load_dwordx4 v[112:115], v[134:135], off offset:128
	global_load_dwordx4 v[116:119], v[134:135], off offset:240
	global_load_dwordx4 v[120:123], v[134:135], off offset:224
	global_load_dwordx4 v[124:127], v[134:135], off offset:208
	global_load_dwordx4 v[240:243], v[134:135], off offset:192
	v_fmac_f32_e32 v7, v72, v72
	v_fmac_f32_e32 v7, v70, v70
	v_fmac_f32_e32 v7, v68, v68
	v_fmac_f32_e32 v7, v65, v65
	v_fmac_f32_e32 v7, v63, v63
	v_fmac_f32_e32 v7, v61, v61
	v_fmac_f32_e32 v7, v59, v59
	v_fmac_f32_e32 v7, v57, v57
	v_fmac_f32_e32 v7, v55, v55
	v_fmac_f32_e32 v7, v49, v49
	v_fmac_f32_e32 v7, v42, v42
	v_fmac_f32_e32 v7, v39, v39
	v_fmac_f32_e32 v7, v35, v35
	v_fmac_f32_e32 v7, v33, v33
	v_fmac_f32_e32 v7, v30, v30
	v_fmac_f32_e32 v7, v27, v27
	s_waitcnt vmcnt(3)
	v_fma_f32 v34, -v130, v34, v100
	s_waitcnt vmcnt(2)
	v_fma_f32 v50, -v130, v50, v104
	s_waitcnt vmcnt(1)
	v_fma_f32 v58, -v130, v58, v110
	s_waitcnt vmcnt(0)
; __device__ __forceinline__ unsigned cvtpk(float lo, float hi) { unsigned r; asm volatile("v_cvt_pk_bf16_f32 %0, %1, %2" : "=v"(r) : "v"(lo), "v"(hi)); return r; }
; __global__ void __launch_bounds__(512, 2) mega(Args a) {
;     ...
;                         for (int r = 0; r < 16; r += 4) { const f32x4 s1 = *(const f32x4*)(sp + d * 16 + r);
; #pragma unroll
;                             for (int k = 0; k < 4; ++k) { const float x = s1[k] - lam * o[d][r + k]; o[d][r + k] = x; ssq += x * x; } }
;                         asm volatile("" ::: "memory"); }
;                     ssq += __shfl_xor(ssq, 32);
;                     const float rs = rsqrtf(ssq * (1.0f / 128.0f) + EPS) * 0.8f;
;                     bf16_t* orow = xn + (size_t)qrow * DM + h * 128 + 4 * hi;
; #pragma unroll
;                     for (int d = 0; d < 4; ++d)
; #pragma unroll
;                         for (int r4 = 0; r4 < 4; ++r4) { const f32x4 gg = *(const f32x4*)(a.in[16] + d * 32 + r4 * 8 + 4 * hi);
;                             u32x2 w; w.x = cvtpk(o[d][4 * r4] * rs * gg[0], o[d][4 * r4 + 1] * rs * gg[1]); w.y = cvtpk(o[d][4 * r4 + 2] * rs * gg[2], o[d][4 * r4 + 3] * rs * gg[3]);
	v_fma_f32 v71, -v130, v71, v112
	v_fma_f32 v69, -v130, v69, v113
	v_fma_f32 v67, -v130, v67, v114
	v_fma_f32 v64, -v130, v64, v115
	v_fma_f32 v56, -v130, v56, v111
	v_fma_f32 v46, -v130, v46, v105
	v_fma_f32 v41, -v130, v41, v106
	v_fma_f32 v38, -v130, v38, v107
	v_fma_f32 v32, -v130, v76, v101
	v_fma_f32 v29, -v130, v29, v102
	v_fma_f32 v26, -v130, v26, v103
	v_fmac_f32_e32 v7, v71, v71
	v_fmac_f32_e32 v7, v69, v69
	v_fmac_f32_e32 v7, v67, v67
	v_fmac_f32_e32 v7, v64, v64
	v_fma_f32 v62, -v130, v62, v108
	v_fmac_f32_e32 v7, v62, v62
	v_fma_f32 v60, -v130, v60, v109
	v_fmac_f32_e32 v7, v60, v60
	v_fmac_f32_e32 v7, v58, v58
	v_fmac_f32_e32 v7, v56, v56
	v_fmac_f32_e32 v7, v50, v50
	v_fmac_f32_e32 v7, v46, v46
	v_fmac_f32_e32 v7, v41, v41
	v_fmac_f32_e32 v7, v38, v38
	v_fmac_f32_e32 v7, v34, v34
	v_fmac_f32_e32 v7, v32, v32
	v_fmac_f32_e32 v7, v29, v29
	v_fmac_f32_e32 v7, v26, v26
	v_pk_mul_f32 v[8:9], v[66:67], v[8:9] op_sel_hi:[0,1]
	v_fma_f32 v78, -v130, v75, v240
	v_fmac_f32_e32 v7, v78, v78
	v_fma_f32 v77, -v130, v74, v241
	v_fmac_f32_e32 v7, v77, v77
	v_fma_f32 v76, -v130, v73, v242
	v_fmac_f32_e32 v7, v76, v76
	v_fma_f32 v75, -v130, v23, v243
	v_fmac_f32_e32 v7, v75, v75
	v_fma_f32 v74, -v130, v22, v124
	v_fmac_f32_e32 v7, v74, v74
	v_fma_f32 v73, -v130, v6, v125
	v_pk_fma_f32 v[22:23], v[130:131], v[8:9], v[126:127] neg_lo:[1, 0, 0] neg_hi:[1, 0, 0]
	v_fmac_f32_e32 v7, v73, v73
	v_pk_mul_f32 v[8:9], v[22:23], v[22:23]
	s_nop 0
	v_add_f32_e32 v6, v7, v8
	v_add_f32_e32 v8, v6, v9
	v_pk_mul_f32 v[6:7], v[66:67], v[10:11] op_sel_hi:[0,1]
	v_pk_fma_f32 v[18:19], v[130:131], v[6:7], v[120:121] neg_lo:[1, 0, 0] neg_hi:[1, 0, 0]
	s_nop 0
	v_pk_mul_f32 v[6:7], v[18:19], v[18:19]
	s_nop 0
	v_add_f32_e32 v6, v8, v6
	v_add_f32_e32 v8, v6, v7
	v_pk_mul_f32 v[6:7], v[66:67], v[12:13] op_sel_hi:[0,1]
	v_pk_fma_f32 v[10:11], v[130:131], v[6:7], v[122:123] neg_lo:[1, 0, 0] neg_hi:[1, 0, 0]
	s_nop 0
	v_pk_mul_f32 v[6:7], v[10:11], v[10:11]
	s_nop 0
	v_add_f32_e32 v6, v8, v6
	v_add_f32_e32 v12, v6, v7
	v_pk_mul_f32 v[6:7], v[66:67], v[14:15] op_sel_hi:[0,1]
	v_pk_fma_f32 v[8:9], v[130:131], v[6:7], v[116:117] neg_lo:[1, 0, 0] neg_hi:[1, 0, 0]
	s_nop 0
	v_pk_mul_f32 v[2:3], v[8:9], v[8:9]
	s_nop 0
	v_add_f32_e32 v2, v12, v2
	v_add_f32_e32 v12, v2, v3
	v_pk_mul_f32 v[2:3], v[66:67], v[16:17] op_sel_hi:[0,1]
	v_pk_fma_f32 v[6:7], v[130:131], v[2:3], v[118:119] neg_lo:[1, 0, 0] neg_hi:[1, 0, 0]
	v_and_b32_e32 v4, 64, v231
	v_pk_mul_f32 v[2:3], v[6:7], v[6:7]
	v_add_u32_e32 v4, 64, v4
	v_add_f32_e32 v2, v12, v2
	v_add_f32_e32 v2, v2, v3
	v_xor_b32_e32 v3, 32, v231
	v_cmp_lt_i32_e32 vcc, v3, v4
	v_lshlrev_b32_e32 v4, 1, v154
	v_mov_b32_e32 v5, v153
	v_cndmask_b32_e32 v3, v231, v3, vcc
	v_lshlrev_b32_e32 v3, 2, v3
	ds_bpermute_b32 v3, v3, v2
	s_waitcnt lgkmcnt(0)
	v_add_f32_e32 v2, v2, v3
	v_fmamk_f32 v2, v2, 0x3c000000, v229
	v_cmp_gt_f32_e32 vcc, s0, v2
	v_mul_f32_e32 v3, 0x4b800000, v2
	v_readlane_b32 s0, v244, 38
	v_cndmask_b32_e32 v2, v2, v3, vcc
	v_rsq_f32_e32 v2, v2
	s_lshl_b32 s4, s0, 1
	v_mul_f32_e32 v3, 0x45800000, v2
	v_cndmask_b32_e32 v2, v2, v3, vcc
	v_mul_f32_e32 v14, 0x3f4ccccd, v2
	v_lshlrev_b64 v[2:3], 12, v[144:145]
	v_lshl_add_u64 v[2:3], s[84:85], 0, v[2:3]
	v_lshl_add_u64 v[2:3], v[2:3], 0, s[4:5]
	v_lshl_add_u64 v[12:13], v[2:3], 0, v[4:5]
	global_load_dwordx4 v[80:83], v[142:143], off
	global_load_dwordx4 v[84:87], v[142:143], off offset:32
	global_load_dwordx4 v[88:91], v[142:143], off offset:64
	global_load_dwordx4 v[92:95], v[142:143], off offset:96
	global_load_dwordx4 v[96:99], v[142:143], off offset:128
	global_load_dwordx4 v[100:103], v[142:143], off offset:160
	global_load_dwordx4 v[104:107], v[142:143], off offset:192
	global_load_dwordx4 v[108:111], v[142:143], off offset:224
	v_mul_f32_e32 v15, v14, v54
	v_mul_f32_e32 v8, v14, v8
	s_waitcnt vmcnt(0)
; __device__ __forceinline__ unsigned cvtpk(float lo, float hi) { unsigned r; asm volatile("v_cvt_pk_bf16_f32 %0, %1, %2" : "=v"(r) : "v"(lo), "v"(hi)); return r; }
; __global__ void __launch_bounds__(512, 2) mega(Args a) {
;     ...
;                     bf16_t* orow = xn + (size_t)qrow * DM + h * 128 + 4 * hi;
; #pragma unroll
;                     for (int d = 0; d < 4; ++d)
; #pragma unroll
;                         for (int r4 = 0; r4 < 4; ++r4) { const f32x4 gg = *(const f32x4*)(a.in[16] + d * 32 + r4 * 8 + 4 * hi);
;                             u32x2 w; w.x = cvtpk(o[d][4 * r4] * rs * gg[0], o[d][4 * r4 + 1] * rs * gg[1]); w.y = cvtpk(o[d][4 * r4 + 2] * rs * gg[2], o[d][4 * r4 + 3] * rs * gg[3]);
;                             *(u32x2*)(orow + d * 32 + r4 * 8) = w; }
	v_mul_f32_e32 v2, v80, v15
	v_mul_f32_e32 v15, v14, v51
	v_mul_f32_e32 v3, v81, v15
	v_cvt_pk_bf16_f32 v2, v2, v3
	v_mul_f32_e32 v3, v14, v52
	v_mul_f32_e32 v3, v82, v3
	v_mul_f32_e32 v4, v14, v53
	v_mul_f32_e32 v4, v83, v4
	v_cvt_pk_bf16_f32 v3, v3, v4
	global_store_dwordx2 v[12:13], v[2:3], off
	v_mul_f32_e32 v15, v14, v47
	v_mul_f32_e32 v2, v84, v15
	v_mul_f32_e32 v15, v14, v48
	v_mul_f32_e32 v3, v85, v15
	v_cvt_pk_bf16_f32 v2, v2, v3
	v_mul_f32_e32 v3, v14, v44
	v_mul_f32_e32 v3, v86, v3
	v_mul_f32_e32 v4, v14, v45
	v_mul_f32_e32 v4, v87, v4
	v_cvt_pk_bf16_f32 v3, v3, v4
	global_store_dwordx2 v[12:13], v[2:3], off offset:16
	v_mul_f32_e32 v15, v14, v43
	v_mul_f32_e32 v2, v88, v15
	v_mul_f32_e32 v15, v14, v40
	v_mul_f32_e32 v3, v89, v15
	v_cvt_pk_bf16_f32 v2, v2, v3
	v_mul_f32_e32 v3, v14, v37
	v_mul_f32_e32 v3, v90, v3
	v_mul_f32_e32 v4, v14, v36
	v_mul_f32_e32 v4, v91, v4
	v_cvt_pk_bf16_f32 v3, v3, v4
	global_store_dwordx2 v[12:13], v[2:3], off offset:32
	v_mul_f32_e32 v15, v14, v31
	v_mul_f32_e32 v2, v92, v15
	v_mul_f32_e32 v15, v14, v28
	v_mul_f32_e32 v3, v93, v15
	v_cvt_pk_bf16_f32 v2, v2, v3
	v_mul_f32_e32 v3, v14, v25
	v_mul_f32_e32 v3, v94, v3
	v_mul_f32_e32 v4, v14, v24
	v_mul_f32_e32 v4, v95, v4
	v_cvt_pk_bf16_f32 v3, v3, v4
	global_store_dwordx2 v[12:13], v[2:3], off offset:48
	v_mul_f32_e32 v15, v14, v72
	v_mul_f32_e32 v2, v96, v15
	v_mul_f32_e32 v15, v14, v70
	v_mul_f32_e32 v3, v97, v15
	v_cvt_pk_bf16_f32 v2, v2, v3
	v_mul_f32_e32 v3, v14, v68
	v_mul_f32_e32 v3, v98, v3
	v_mul_f32_e32 v4, v14, v65
	v_mul_f32_e32 v4, v99, v4
	v_cvt_pk_bf16_f32 v3, v3, v4
	global_store_dwordx2 v[12:13], v[2:3], off offset:64
	v_mul_f32_e32 v15, v14, v63
	v_mul_f32_e32 v2, v100, v15
	v_mul_f32_e32 v15, v14, v61
	v_mul_f32_e32 v3, v101, v15
	v_cvt_pk_bf16_f32 v2, v2, v3
	v_mul_f32_e32 v3, v14, v59
	v_mul_f32_e32 v3, v102, v3
	v_mul_f32_e32 v4, v14, v57
	v_mul_f32_e32 v4, v103, v4
	v_cvt_pk_bf16_f32 v3, v3, v4
	global_store_dwordx2 v[12:13], v[2:3], off offset:80
	v_mul_f32_e32 v15, v14, v55
	v_mul_f32_e32 v2, v104, v15
	v_mul_f32_e32 v15, v14, v49
	v_mul_f32_e32 v3, v105, v15
	v_cvt_pk_bf16_f32 v2, v2, v3
	v_mul_f32_e32 v3, v14, v42
	v_mul_f32_e32 v3, v106, v3
	v_mul_f32_e32 v4, v14, v39
	v_mul_f32_e32 v4, v107, v4
	v_cvt_pk_bf16_f32 v3, v3, v4
	global_store_dwordx2 v[12:13], v[2:3], off offset:96
	v_mul_f32_e32 v15, v14, v35
	v_mul_f32_e32 v2, v108, v15
	v_mul_f32_e32 v15, v14, v33
	v_mul_f32_e32 v3, v109, v15
	v_cvt_pk_bf16_f32 v2, v2, v3
	v_mul_f32_e32 v3, v14, v30
	v_mul_f32_e32 v3, v110, v3
	v_mul_f32_e32 v4, v14, v27
	v_mul_f32_e32 v4, v111, v4
	v_cvt_pk_bf16_f32 v3, v3, v4
	global_store_dwordx2 v[12:13], v[2:3], off offset:112
	global_load_dwordx4 v[80:83], v[142:143], off offset:256
	global_load_dwordx4 v[84:87], v[142:143], off offset:288
	global_load_dwordx4 v[88:91], v[142:143], off offset:320
	global_load_dwordx4 v[92:95], v[142:143], off offset:352
	global_load_dwordx4 v[96:99], v[142:143], off offset:384
	global_load_dwordx4 v[100:103], v[142:143], off offset:416
	global_load_dwordx4 v[104:107], v[142:143], off offset:448
	global_load_dwordx4 v[108:111], v[142:143], off offset:480
	v_mul_f32_e32 v15, v14, v71
	s_waitcnt vmcnt(0)
	v_mul_f32_e32 v2, v80, v15
	v_mul_f32_e32 v15, v14, v69
	v_mul_f32_e32 v3, v81, v15
	v_cvt_pk_bf16_f32 v2, v2, v3
	v_mul_f32_e32 v3, v14, v67
	v_mul_f32_e32 v3, v82, v3
	v_mul_f32_e32 v4, v14, v64
	v_mul_f32_e32 v4, v83, v4
	v_cvt_pk_bf16_f32 v3, v3, v4
	global_store_dwordx2 v[12:13], v[2:3], off offset:128
	v_mul_f32_e32 v15, v14, v62
	v_mul_f32_e32 v2, v84, v15
	v_mul_f32_e32 v15, v14, v60
	v_mul_f32_e32 v3, v85, v15
	v_cvt_pk_bf16_f32 v2, v2, v3
	v_mul_f32_e32 v3, v14, v58
	v_mul_f32_e32 v3, v86, v3
	v_mul_f32_e32 v4, v14, v56
	v_mul_f32_e32 v4, v87, v4
	v_cvt_pk_bf16_f32 v3, v3, v4
	global_store_dwordx2 v[12:13], v[2:3], off offset:144
	v_mul_f32_e32 v15, v14, v50
	v_mul_f32_e32 v2, v88, v15
	v_mul_f32_e32 v15, v14, v46
	v_mul_f32_e32 v3, v89, v15
	v_cvt_pk_bf16_f32 v2, v2, v3
	v_mul_f32_e32 v3, v14, v41
	v_mul_f32_e32 v3, v90, v3
	v_mul_f32_e32 v4, v14, v38
	v_mul_f32_e32 v4, v91, v4
	v_cvt_pk_bf16_f32 v3, v3, v4
	global_store_dwordx2 v[12:13], v[2:3], off offset:160
	v_mul_f32_e32 v15, v14, v34
	v_mul_f32_e32 v2, v92, v15
	v_mul_f32_e32 v15, v14, v32
	v_mul_f32_e32 v3, v93, v15
	v_cvt_pk_bf16_f32 v2, v2, v3
	v_mul_f32_e32 v3, v14, v29
	v_mul_f32_e32 v3, v94, v3
	v_mul_f32_e32 v4, v14, v26
	v_mul_f32_e32 v4, v95, v4
	v_cvt_pk_bf16_f32 v3, v3, v4
	global_store_dwordx2 v[12:13], v[2:3], off offset:176
	v_mul_f32_e32 v15, v14, v78
	v_mul_f32_e32 v2, v96, v15
	v_mul_f32_e32 v15, v14, v77
	v_mul_f32_e32 v3, v97, v15
	v_cvt_pk_bf16_f32 v2, v2, v3
	v_mul_f32_e32 v3, v14, v76
	v_mul_f32_e32 v3, v98, v3
	v_mul_f32_e32 v4, v14, v75
	v_mul_f32_e32 v4, v99, v4
	v_cvt_pk_bf16_f32 v3, v3, v4
	global_store_dwordx2 v[12:13], v[2:3], off offset:192
	v_mul_f32_e32 v15, v14, v74
	v_mul_f32_e32 v2, v100, v15
	v_mul_f32_e32 v15, v14, v73
	v_mul_f32_e32 v3, v101, v15
	v_cvt_pk_bf16_f32 v2, v2, v3
	v_mul_f32_e32 v3, v14, v22
	v_mul_f32_e32 v3, v102, v3
	v_mul_f32_e32 v4, v14, v23
	v_mul_f32_e32 v4, v103, v4
	v_cvt_pk_bf16_f32 v3, v3, v4
	global_store_dwordx2 v[12:13], v[2:3], off offset:208
	v_mul_f32_e32 v15, v14, v18
	v_mul_f32_e32 v2, v104, v15
	v_mul_f32_e32 v15, v14, v19
	v_mul_f32_e32 v3, v105, v15
	v_cvt_pk_bf16_f32 v2, v2, v3
	v_mul_f32_e32 v3, v14, v10
	v_mul_f32_e32 v3, v106, v3
	v_mul_f32_e32 v4, v14, v11
	v_mul_f32_e32 v4, v107, v4
	v_cvt_pk_bf16_f32 v3, v3, v4
	global_store_dwordx2 v[12:13], v[2:3], off offset:224
	v_mul_f32_e32 v2, v108, v8
	v_mul_f32_e32 v8, v14, v9
	v_mul_f32_e32 v3, v109, v8
	v_cvt_pk_bf16_f32 v2, v2, v3
	v_mul_f32_e32 v3, v14, v6
	v_mul_f32_e32 v3, v110, v3
	v_mul_f32_e32 v4, v14, v7
	v_mul_f32_e32 v4, v111, v4
	v_cvt_pk_bf16_f32 v3, v3, v4
	global_store_dwordx2 v[12:13], v[2:3], off offset:240
	s_branch .LBB0_1168
